# hand-written phase 0 weight conversion: per-wave 64x64 tiles via LDS-DMA with source-side swizzle, no workgroup barriers
# baseline (speedup 1.0000x reference)
; __device__ __forceinline__ WDesc wdesc(const Params& p, int l, int u) {
;     unsigned char* ws = p.ws;
;     constexpr int T_IN = 44 * 16, T_OUT = 16 * 16, T_GU = 88 * 16, T_D = 16 * 44;
;     WDesc d; int v = u;
;     if (v < T_IN) { const int rt = v / 16, kt = v % 16; int nv = DIN - rt * 64; nv = nv > 64 ? 64 : (nv < 0 ? 0 : nv);
;         d.src = p.in[3] + (size_t)l * D * DIN; d.ldsrc = DIN; d.c0 = nv > 0 ? rt * 64 : 0; d.nvalid = nv; d.k0 = kt * 64; d.dst = (bf16_t*)(ws + WS_WIN); d.lddst = D; d.r0 = rt * 64; return d; }
;     v -= T_IN;
;     if (v < T_OUT) { const int rt = v / 16, kt = v % 16; d.src = p.in[15] + (size_t)l * D * D; d.ldsrc = D; d.c0 = rt * 64; d.nvalid = 64; d.k0 = kt * 64; d.dst = (bf16_t*)(ws + WS_WOUT); d.lddst = D; d.r0 = rt * 64; return d; }
;     v -= T_OUT;
;     if (v < T_GU) { const int rt = v / 16, kt = v % 16; const int r0 = rt * 64, j = r0 / 256, within = r0 % 256;
;         d.src = (within < 128 ? p.in[18] : p.in[19]) + (size_t)l * D * DFF; d.ldsrc = DFF; d.c0 = j * 128 + (within & 127); d.nvalid = 64; d.k0 = kt * 64; d.dst = (bf16_t*)(ws + WS_WGU); d.lddst = D; d.r0 = r0; return d; }
;     v -= T_GU;
;     if (v < T_D) { const int rt = v / 44, kt = v % 44; d.src = p.in[20] + (size_t)l * DFF * D; d.ldsrc = D; d.c0 = rt * 64; d.nvalid = 64; d.k0 = kt * 64; d.dst = (bf16_t*)(ws + WS_WD); d.lddst = DFF; d.r0 = rt * 64; return d; }
;     v -= T_D;
;     { const int dir = v / 16, gate = (v / 8) % 2, h = v % 8; d.src = (gate ? p.in[8] : p.in[6]) + ((size_t)(l * 2 + dir) * 8 + h) * 4096; d.ldsrc = 64; d.c0 = 0; d.nvalid = 64; d.k0 = 0;
;       d.dst = (bf16_t*)(ws + WS_LRUW) + ((size_t)(dir * 2 + gate) * 8 + h) * 4096; d.lddst = 64; d.r0 = 0; return d; }
; }
; __device__ void phase_weights(const Params& p, int l, LAS unsigned char* lds) {
;     LAS float* T = (LAS float*)lds;
;     unsigned char* ws = p.ws;
;     constexpr int TOT = 44 * 16 + 16 * 16 + 88 * 16 + 16 * 44 + 32;
;     const int tid = otid(), G = gridDim.x;
;     for (int u0 = obid(); u0 < TOT; u0 += 4 * G) {
;         f32x4 v[4][2];
;         { const int k = tid >> 3, cg8 = (tid & 7) * 8;
; #pragma unroll
;           for (int j = 0; j < 4; ++j) { const int u = u0 + j * G; v[j][0] = (f32x4){0.f, 0.f, 0.f, 0.f}; v[j][1] = v[j][0];
;               if (u < TOT) { const WDesc d = wdesc(p, l, u); const float* sp = d.src + (size_t)(d.k0 + k) * d.ldsrc + d.c0 + cg8;
.LBB0_377:
	v_and_b32_e32 v0, 63, v245
	v_readfirstlane_b32 s20, v245
	v_readlane_b32 s51, v255, 16
	v_readlane_b32 s4, v254, 33
	v_readlane_b32 s5, v254, 34
	v_readlane_b32 s6, v254, 57
	v_readlane_b32 s7, v254, 58
	v_readlane_b32 s8, v253, 4
	v_readlane_b32 s9, v253, 5
	v_readlane_b32 s10, v253, 6
	v_readlane_b32 s11, v253, 7
	v_readlane_b32 s12, v254, 60
	v_readlane_b32 s13, v254, 61
	v_readlane_b32 s14, v254, 39
	v_readlane_b32 s15, v254, 40
	v_readlane_b32 s16, v254, 43
	v_readlane_b32 s17, v254, 44
	v_readlane_b32 s18, v255, 0
	v_readlane_b32 s19, v255, 1
	v_readlane_b32 s52, v255, 8
	v_readlane_b32 s53, v255, 9
	s_mov_b32 s21, s2
	s_lshr_b32 s20, s20, 6
	s_lshl_b32 s31, s20, 14
	s_load_dword s26, s[52:53], 0x0
	s_mul_i32 s0, s51, 0xa20000
	s_add_u32 s4, s4, s0
	s_addc_u32 s5, s5, 0
	s_lshl_b32 s0, s51, 22
	s_add_u32 s6, s6, s0
	s_addc_u32 s7, s7, 0
	s_mul_i32 s0, s51, 0xb00000
	s_add_u32 s8, s8, s0
	s_addc_u32 s9, s9, 0
	s_add_u32 s10, s10, s0
	s_addc_u32 s11, s11, 0
	s_add_u32 s12, s12, s0
	s_addc_u32 s13, s13, 0
	s_lshl_b32 s0, s51, 18
	s_add_u32 s14, s14, s0
	s_addc_u32 s15, s15, 0
	s_add_u32 s16, s16, s0
	s_addc_u32 s17, s17, 0
	v_lshrrev_b32_e32 v1, 4, v0
	v_and_b32_e32 v22, 15, v0
	v_xor_b32_e32 v2, 0, v22
	v_lshlrev_b32_e32 v2, 4, v2
	v_xor_b32_e32 v3, 1, v22
	v_lshlrev_b32_e32 v3, 4, v3
	v_xor_b32_e32 v4, 2, v22
	v_lshlrev_b32_e32 v4, 4, v4
	v_xor_b32_e32 v5, 3, v22
	v_lshlrev_b32_e32 v5, 4, v5
	v_xor_b32_e32 v6, 4, v22
	v_lshlrev_b32_e32 v6, 4, v6
	v_xor_b32_e32 v7, 5, v22
	v_lshlrev_b32_e32 v7, 4, v7
	v_xor_b32_e32 v8, 6, v22
	v_lshlrev_b32_e32 v8, 4, v8
	v_xor_b32_e32 v9, 7, v22
	v_lshlrev_b32_e32 v9, 4, v9
	v_lshrrev_b32_e32 v10, 3, v0
	v_and_b32_e32 v11, 7, v0
	v_lshrrev_b32_e32 v22, 2, v10
	v_and_b32_e32 v23, 3, v10
	v_lshlrev_b32_e32 v23, 2, v23
	v_lshl_add_u32 v23, v11, 11, v23
	v_add_u32_e32 v23, s31, v23
	v_add_u32_e32 v12, 0, v22
	v_xor_b32_e32 v12, v12, v11
	v_lshl_add_u32 v12, v12, 4, v23
	v_add_u32_e32 v13, 2, v22
	v_xor_b32_e32 v13, v13, v11
	v_lshl_add_u32 v13, v13, 4, v23
	v_add_u32_e32 v14, 4, v22
	v_xor_b32_e32 v14, v14, v11
	v_lshl_add_u32 v14, v14, 4, v23
	v_add_u32_e32 v15, 6, v22
	v_xor_b32_e32 v15, v15, v11
	v_lshl_add_u32 v15, v15, 4, v23
	v_add_u32_e32 v16, 8, v22
	v_xor_b32_e32 v16, v16, v11
	v_lshl_add_u32 v16, v16, 4, v23
	v_add_u32_e32 v17, 10, v22
	v_xor_b32_e32 v17, v17, v11
	v_lshl_add_u32 v17, v17, 4, v23
	v_add_u32_e32 v18, 12, v22
	v_xor_b32_e32 v18, v18, v11
	v_lshl_add_u32 v18, v18, 4, v23
	v_add_u32_e32 v19, 14, v22
	v_xor_b32_e32 v19, v19, v11
	v_lshl_add_u32 v19, v19, 4, v23
	s_waitcnt lgkmcnt(0)
	s_mov_b32 s27, 0
.Lwt_round:
	s_lshl_b32 s30, s20, 8
	s_add_u32 s30, s30, s21
	s_cmp_eq_u32 s27, 0
	s_cbranch_scc1 .Lwt_decode
	s_add_u32 s30, s30, 0x800
	s_cmp_lt_u32 s20, 4
	s_cbranch_scc1 .Lwt_decode
	s_cmp_lg_u32 s20, 4
	s_cbranch_scc1 .Lwt_done
	s_cmp_gt_u32 s21, 31
	s_cbranch_scc1 .Lwt_done
	s_add_u32 s30, s21, 0xc00
.Lwt_decode:
	s_mov_b32 s34, 8
	s_cmpk_lt_u32 s30, 0x2c0
	s_cbranch_scc1 .Lwt_in
	s_cmpk_lt_u32 s30, 0x3c0
	s_cbranch_scc1 .Lwt_out
	s_cmpk_lt_u32 s30, 0x940
	s_cbranch_scc1 .Lwt_gu
	s_cmpk_lt_u32 s30, 0xc00
	s_cbranch_scc1 .Lwt_d
	s_sub_u32 s0, s30, 0xc00
	s_mov_b64 s[38:39], s[14:15]
	s_bitcmp1_b32 s0, 3
	s_cselect_b32 s38, s16, s38
	s_cselect_b32 s39, s17, s39
	s_lshr_b32 s1, s0, 4
	s_lshl_b32 s1, s1, 3
	s_and_b32 s43, s0, 7
	s_add_u32 s1, s1, s43
	s_lshl_b32 s1, s1, 14
	s_add_u32 s38, s38, s1
	s_addc_u32 s39, s39, 0
	s_movk_i32 s40, 0x100
	s_movk_i32 s41, 0x80
	s_lshl_b32 s1, s0, 13
	s_add_u32 s44, s18, s1
	s_addc_u32 s45, s19, 0
	s_add_u32 s44, s44, 0x1810000
	s_addc_u32 s45, s45, 0
	s_branch .Lwt_go
.Lwt_in:
	s_lshr_b32 s0, s30, 4
	s_and_b32 s1, s30, 15
	s_mul_i32 s43, s1, 0xa2000
	s_lshl_b32 s48, s0, 8
	s_add_u32 s43, s43, s48
	s_add_u32 s38, s4, s43
	s_addc_u32 s39, s5, 0
	s_movk_i32 s40, 0x2880
	s_movk_i32 s41, 0x800
	s_lshl_b32 s43, s0, 17
	s_lshl_b32 s48, s1, 7
	s_add_u32 s43, s43, s48
	s_add_u32 s44, s18, s43
	s_addc_u32 s45, s19, 0
	s_add_u32 s44, s44, 0x10000
	s_addc_u32 s45, s45, 0
	s_cmp_lt_u32 s0, 40
	s_cbranch_scc1 .Lwt_go
	s_mov_b32 s34, 4
	s_cmp_eq_u32 s0, 40
	s_cbranch_scc1 .Lwt_go
	s_mov_b32 s34, 0
	s_branch .Lwt_go
.Lwt_out:
	s_sub_u32 s0, s30, 0x2c0
	s_and_b32 s1, s0, 15
	s_lshr_b32 s0, s0, 4
	s_lshl_b32 s43, s1, 18
	s_lshl_b32 s48, s0, 8
	s_add_u32 s43, s43, s48
	s_add_u32 s38, s6, s43
	s_addc_u32 s39, s7, 0
	s_movk_i32 s40, 0x1000
	s_movk_i32 s41, 0x800
	s_lshl_b32 s43, s0, 17
	s_lshl_b32 s48, s1, 7
	s_add_u32 s43, s43, s48
	s_add_u32 s44, s18, s43
	s_addc_u32 s45, s19, 0
	s_add_u32 s44, s44, 0x590000
	s_addc_u32 s45, s45, 0
	s_branch .Lwt_go
.Lwt_gu:
	s_sub_u32 s0, s30, 0x3c0
	s_and_b32 s1, s0, 15
	s_lshr_b32 s0, s0, 4
	s_mov_b64 s[38:39], s[8:9]
	s_bitcmp1_b32 s0, 1
	s_cselect_b32 s38, s10, s38
	s_cselect_b32 s39, s11, s39
	s_mul_i32 s43, s1, 0xb0000
	s_lshr_b32 s48, s0, 2
	s_lshl_b32 s48, s48, 9
	s_add_u32 s43, s43, s48
	s_and_b32 s48, s0, 1
	s_lshl_b32 s48, s48, 8
	s_add_u32 s43, s43, s48
	s_add_u32 s38, s38, s43
	s_addc_u32 s39, s39, 0
	s_movk_i32 s40, 0x2c00
	s_movk_i32 s41, 0x800
	s_lshl_b32 s43, s0, 17
	s_lshl_b32 s48, s1, 7
	s_add_u32 s43, s43, s48
	s_add_u32 s44, s18, s43
	s_addc_u32 s45, s19, 0
	s_add_u32 s44, s44, 0x790000
	s_addc_u32 s45, s45, 0
	s_branch .Lwt_go
.Lwt_d:
	s_sub_u32 s0, s30, 0x940
	s_mul_i32 s1, s0, 1490
	s_lshr_b32 s1, s1, 16
	s_mul_i32 s43, s1, 44
	s_sub_u32 s0, s0, s43
	s_lshl_b32 s43, s0, 18
	s_lshl_b32 s48, s1, 8
	s_add_u32 s43, s43, s48
	s_add_u32 s38, s12, s43
	s_addc_u32 s39, s13, 0
	s_movk_i32 s40, 0x1000
	s_movk_i32 s41, 0x1600
	s_mul_i32 s43, s1, 0x58000
	s_lshl_b32 s48, s0, 7
	s_add_u32 s43, s43, s48
	s_add_u32 s44, s18, s43
	s_addc_u32 s45, s19, 0
	s_add_u32 s44, s44, 0x1290000
	s_addc_u32 s45, s45, 0
; #define LAS __attribute__((address_space(3)))
; __device__ __forceinline__ unsigned cvtpk(float lo, float hi) { const f32x2 v = (f32x2){lo, hi}; const bf16v2 b = __builtin_convertvector(v, bf16v2); return __builtin_bit_cast(unsigned, b); }
; __device__ void phase_weights(const Params& p, int l, LAS unsigned char* lds) {
;     ...
;         { const int k = tid >> 3, cg8 = (tid & 7) * 8;
; #pragma unroll
;           for (int j = 0; j < 4; ++j) { const int u = u0 + j * G; v[j][0] = (f32x4){0.f, 0.f, 0.f, 0.f}; v[j][1] = v[j][0];
;               if (u < TOT) { const WDesc d = wdesc(p, l, u); const float* sp = d.src + (size_t)(d.k0 + k) * d.ldsrc + d.c0 + cg8;
;                   if (cg8 + 3 < d.nvalid) v[j][0] = __builtin_nontemporal_load((const f32x4*)sp); if (cg8 + 7 < d.nvalid) v[j][1] = __builtin_nontemporal_load((const f32x4*)(sp + 4)); } }
; #pragma unroll
;           for (int j = 0; j < 4; ++j)
; #pragma unroll
;               for (int i = 0; i < 2; ++i) { LAS float* Tj = T + j * 4160 + k * 65 + cg8 + 4 * i; Tj[0] = v[j][i][0]; Tj[1] = v[j][i][1]; Tj[2] = v[j][i][2]; Tj[3] = v[j][i][3]; } }
;         __syncthreads();
;         { const int r = tid >> 3, kg = (tid & 7) * 8;
; #pragma unroll
;           for (int j = 0; j < 4; ++j) { const int u = u0 + j * G;
;               if (u < TOT) { const WDesc d = wdesc(p, l, u); const LAS float* Tj = T + j * 4160; u32x4 w;
;                   w.x = cvtpk(Tj[(kg + 0) * 65 + r], Tj[(kg + 1) * 65 + r]); w.y = cvtpk(Tj[(kg + 2) * 65 + r], Tj[(kg + 3) * 65 + r]);
;                   w.z = cvtpk(Tj[(kg + 4) * 65 + r], Tj[(kg + 5) * 65 + r]); w.w = cvtpk(Tj[(kg + 6) * 65 + r], Tj[(kg + 7) * 65 + r]);
;                   *(u32x4*)(d.dst + (size_t)(d.r0 + r) * d.lddst + d.k0 + kg) = w; } } }
.Lwt_go:
	v_mul_lo_u32 v20, v1, s40
	v_mul_lo_u32 v21, v10, s41
	v_lshl_add_u32 v21, v11, 4, v21
	s_lshl_b32 s0, s40, 2
	s_lshl_b32 s1, s41, 3
	s_waitcnt lgkmcnt(0)
	s_cmp_eq_u32 s34, 0
	s_cbranch_scc1 .Lwt_rd
	s_mov_b64 s[46:47], exec
	s_add_i32 m0, s31, 0x0
	v_add_u32_e32 v22, v20, v2
	s_cmp_eq_u32 s34, 8
	s_cbranch_scc1 .Lwt_f0
	v_cmp_gt_u32_e32 vcc, 0x80, v2
	s_and_b64 exec, s[46:47], vcc
.Lwt_f0:
	global_load_lds_dwordx4 v22, s[38:39]
	s_add_u32 s38, s38, s0
	s_addc_u32 s39, s39, 0
	s_add_i32 m0, s31, 0x400
	v_add_u32_e32 v23, v20, v2
	global_load_lds_dwordx4 v23, s[38:39]
	s_add_u32 s38, s38, s0
	s_addc_u32 s39, s39, 0
	s_add_i32 m0, s31, 0x800
	v_add_u32_e32 v22, v20, v3
	s_cmp_eq_u32 s34, 8
	s_cbranch_scc1 .Lwt_f2
	v_cmp_gt_u32_e32 vcc, 0x80, v3
	s_and_b64 exec, s[46:47], vcc
.Lwt_f2:
	global_load_lds_dwordx4 v22, s[38:39]
	s_add_u32 s38, s38, s0
	s_addc_u32 s39, s39, 0
	s_add_i32 m0, s31, 0xc00
	v_add_u32_e32 v23, v20, v3
	global_load_lds_dwordx4 v23, s[38:39]
	s_add_u32 s38, s38, s0
	s_addc_u32 s39, s39, 0
	s_add_i32 m0, s31, 0x1000
	v_add_u32_e32 v22, v20, v4
	s_cmp_eq_u32 s34, 8
	s_cbranch_scc1 .Lwt_f4
	v_cmp_gt_u32_e32 vcc, 0x80, v4
	s_and_b64 exec, s[46:47], vcc
.Lwt_f4:
	global_load_lds_dwordx4 v22, s[38:39]
	s_add_u32 s38, s38, s0
	s_addc_u32 s39, s39, 0
	s_add_i32 m0, s31, 0x1400
	v_add_u32_e32 v23, v20, v4
	global_load_lds_dwordx4 v23, s[38:39]
	s_add_u32 s38, s38, s0
	s_addc_u32 s39, s39, 0
	s_add_i32 m0, s31, 0x1800
	v_add_u32_e32 v22, v20, v5
	s_cmp_eq_u32 s34, 8
	s_cbranch_scc1 .Lwt_f6
	v_cmp_gt_u32_e32 vcc, 0x80, v5
	s_and_b64 exec, s[46:47], vcc
.Lwt_f6:
	global_load_lds_dwordx4 v22, s[38:39]
	s_add_u32 s38, s38, s0
	s_addc_u32 s39, s39, 0
	s_add_i32 m0, s31, 0x1c00
	v_add_u32_e32 v23, v20, v5
	global_load_lds_dwordx4 v23, s[38:39]
	s_add_u32 s38, s38, s0
	s_addc_u32 s39, s39, 0
	s_add_i32 m0, s31, 0x2000
	v_add_u32_e32 v22, v20, v6
	s_cmp_eq_u32 s34, 8
	s_cbranch_scc1 .Lwt_f8
	v_cmp_gt_u32_e32 vcc, 0x80, v6
	s_and_b64 exec, s[46:47], vcc
.Lwt_f8:
	global_load_lds_dwordx4 v22, s[38:39]
	s_add_u32 s38, s38, s0
	s_addc_u32 s39, s39, 0
	s_add_i32 m0, s31, 0x2400
	v_add_u32_e32 v23, v20, v6
	global_load_lds_dwordx4 v23, s[38:39]
	s_add_u32 s38, s38, s0
	s_addc_u32 s39, s39, 0
	s_add_i32 m0, s31, 0x2800
	v_add_u32_e32 v22, v20, v7
	s_cmp_eq_u32 s34, 8
	s_cbranch_scc1 .Lwt_f10
	v_cmp_gt_u32_e32 vcc, 0x80, v7
	s_and_b64 exec, s[46:47], vcc
.Lwt_f10:
	global_load_lds_dwordx4 v22, s[38:39]
	s_add_u32 s38, s38, s0
	s_addc_u32 s39, s39, 0
	s_add_i32 m0, s31, 0x2c00
	v_add_u32_e32 v23, v20, v7
	global_load_lds_dwordx4 v23, s[38:39]
	s_add_u32 s38, s38, s0
	s_addc_u32 s39, s39, 0
	s_add_i32 m0, s31, 0x3000
	v_add_u32_e32 v22, v20, v8
	s_cmp_eq_u32 s34, 8
	s_cbranch_scc1 .Lwt_f12
	v_cmp_gt_u32_e32 vcc, 0x80, v8
	s_and_b64 exec, s[46:47], vcc
.Lwt_f12:
	global_load_lds_dwordx4 v22, s[38:39]
	s_add_u32 s38, s38, s0
	s_addc_u32 s39, s39, 0
	s_add_i32 m0, s31, 0x3400
	v_add_u32_e32 v23, v20, v8
	global_load_lds_dwordx4 v23, s[38:39]
	s_add_u32 s38, s38, s0
	s_addc_u32 s39, s39, 0
	s_add_i32 m0, s31, 0x3800
	v_add_u32_e32 v22, v20, v9
	s_cmp_eq_u32 s34, 8
	s_cbranch_scc1 .Lwt_f14
	v_cmp_gt_u32_e32 vcc, 0x80, v9
	s_and_b64 exec, s[46:47], vcc
.Lwt_f14:
	global_load_lds_dwordx4 v22, s[38:39]
	s_add_u32 s38, s38, s0
	s_addc_u32 s39, s39, 0
	s_add_i32 m0, s31, 0x3c00
	v_add_u32_e32 v23, v20, v9
	global_load_lds_dwordx4 v23, s[38:39]
	s_add_u32 s38, s38, s0
	s_addc_u32 s39, s39, 0
	s_mov_b64 exec, s[46:47]
.Lwt_rd:
	s_waitcnt vmcnt(0)
	s_cmp_lt_u32 s34, 1
	s_cbranch_scc1 .Lwt_r0
	ds_read_b32 v24, v12
	ds_read_b32 v25, v12 offset:256
	ds_read_b32 v26, v12 offset:512
	ds_read_b32 v27, v12 offset:768
	ds_read_b32 v28, v12 offset:1024
	ds_read_b32 v29, v12 offset:1280
	ds_read_b32 v30, v12 offset:1536
	ds_read_b32 v31, v12 offset:1792
.Lwt_r0:
	s_waitcnt lgkmcnt(0)
	s_cmp_lt_u32 s34, 2
	s_cbranch_scc1 .Lwt_n0
	ds_read_b32 v32, v13
	ds_read_b32 v33, v13 offset:256
	ds_read_b32 v34, v13 offset:512
	ds_read_b32 v35, v13 offset:768
	ds_read_b32 v36, v13 offset:1024
	ds_read_b32 v37, v13 offset:1280
	ds_read_b32 v38, v13 offset:1536
	ds_read_b32 v39, v13 offset:1792
.Lwt_n0:
	s_cmp_lt_u32 s34, 1
	s_cbranch_scc1 .Lwt_z0
	v_cvt_pk_bf16_f32 v40, v24, v25
	v_cvt_pk_bf16_f32 v41, v26, v27
	v_cvt_pk_bf16_f32 v42, v28, v29
	v_cvt_pk_bf16_f32 v43, v30, v31
	s_branch .Lwt_s0
.Lwt_z0:
	v_mov_b32_e32 v40, 0
	v_mov_b32_e32 v41, 0
	v_mov_b32_e32 v42, 0
	v_mov_b32_e32 v43, 0
.Lwt_s0:
	global_store_dwordx4 v21, v[40:43], s[44:45]
	s_add_u32 s44, s44, s1
	s_addc_u32 s45, s45, 0
	s_waitcnt lgkmcnt(0)
	s_cmp_lt_u32 s34, 3
	s_cbranch_scc1 .Lwt_n1
	ds_read_b32 v24, v14
	ds_read_b32 v25, v14 offset:256
	ds_read_b32 v26, v14 offset:512
	ds_read_b32 v27, v14 offset:768
	ds_read_b32 v28, v14 offset:1024
	ds_read_b32 v29, v14 offset:1280
	ds_read_b32 v30, v14 offset:1536
	ds_read_b32 v31, v14 offset:1792
.Lwt_n1:
	s_cmp_lt_u32 s34, 2
	s_cbranch_scc1 .Lwt_z1
	v_cvt_pk_bf16_f32 v44, v32, v33
	v_cvt_pk_bf16_f32 v45, v34, v35
	v_cvt_pk_bf16_f32 v46, v36, v37
	v_cvt_pk_bf16_f32 v47, v38, v39
	s_branch .Lwt_s1
.Lwt_z1:
	v_mov_b32_e32 v44, 0
	v_mov_b32_e32 v45, 0
	v_mov_b32_e32 v46, 0
	v_mov_b32_e32 v47, 0
.Lwt_s1:
	global_store_dwordx4 v21, v[44:47], s[44:45]
	s_add_u32 s44, s44, s1
	s_addc_u32 s45, s45, 0
	s_waitcnt lgkmcnt(0)
	s_cmp_lt_u32 s34, 4
	s_cbranch_scc1 .Lwt_n2
	ds_read_b32 v32, v15
	ds_read_b32 v33, v15 offset:256
	ds_read_b32 v34, v15 offset:512
	ds_read_b32 v35, v15 offset:768
	ds_read_b32 v36, v15 offset:1024
	ds_read_b32 v37, v15 offset:1280
	ds_read_b32 v38, v15 offset:1536
	ds_read_b32 v39, v15 offset:1792
.Lwt_n2:
	s_cmp_lt_u32 s34, 3
	s_cbranch_scc1 .Lwt_z2
	v_cvt_pk_bf16_f32 v40, v24, v25
	v_cvt_pk_bf16_f32 v41, v26, v27
	v_cvt_pk_bf16_f32 v42, v28, v29
	v_cvt_pk_bf16_f32 v43, v30, v31
	s_branch .Lwt_s2

; #define LAS __attribute__((address_space(3)))
; __device__ __forceinline__ unsigned cvtpk(float lo, float hi) { const f32x2 v = (f32x2){lo, hi}; const bf16v2 b = __builtin_convertvector(v, bf16v2); return __builtin_bit_cast(unsigned, b); }
; __device__ void phase_weights(const Params& p, int l, LAS unsigned char* lds) {
;     ...
;         { const int r = tid >> 3, kg = (tid & 7) * 8;
; #pragma unroll
;           for (int j = 0; j < 4; ++j) { const int u = u0 + j * G;
;               if (u < TOT) { const WDesc d = wdesc(p, l, u); const LAS float* Tj = T + j * 4160; u32x4 w;
;                   w.x = cvtpk(Tj[(kg + 0) * 65 + r], Tj[(kg + 1) * 65 + r]); w.y = cvtpk(Tj[(kg + 2) * 65 + r], Tj[(kg + 3) * 65 + r]);
;                   w.z = cvtpk(Tj[(kg + 4) * 65 + r], Tj[(kg + 5) * 65 + r]); w.w = cvtpk(Tj[(kg + 6) * 65 + r], Tj[(kg + 7) * 65 + r]);
;                   *(u32x4*)(d.dst + (size_t)(d.r0 + r) * d.lddst + d.k0 + kg) = w; } } }
.Lwt_s2:
	global_store_dwordx4 v21, v[40:43], s[44:45]
	s_add_u32 s44, s44, s1
	s_addc_u32 s45, s45, 0
	s_waitcnt lgkmcnt(0)
	s_cmp_lt_u32 s34, 5
	s_cbranch_scc1 .Lwt_n3
	ds_read_b32 v24, v16
	ds_read_b32 v25, v16 offset:256
	ds_read_b32 v26, v16 offset:512
	ds_read_b32 v27, v16 offset:768
	ds_read_b32 v28, v16 offset:1024
	ds_read_b32 v29, v16 offset:1280
	ds_read_b32 v30, v16 offset:1536
	ds_read_b32 v31, v16 offset:1792
.Lwt_n3:
	s_cmp_lt_u32 s34, 4
	s_cbranch_scc1 .Lwt_z3
	v_cvt_pk_bf16_f32 v44, v32, v33
	v_cvt_pk_bf16_f32 v45, v34, v35
	v_cvt_pk_bf16_f32 v46, v36, v37
	v_cvt_pk_bf16_f32 v47, v38, v39
	s_branch .Lwt_s3

; #define LAS __attribute__((address_space(3)))
; __device__ __forceinline__ unsigned cvtpk(float lo, float hi) { const f32x2 v = (f32x2){lo, hi}; const bf16v2 b = __builtin_convertvector(v, bf16v2); return __builtin_bit_cast(unsigned, b); }
; __device__ void phase_weights(const Params& p, int l, LAS unsigned char* lds) {
;     ...
;         { const int r = tid >> 3, kg = (tid & 7) * 8;
; #pragma unroll
;           for (int j = 0; j < 4; ++j) { const int u = u0 + j * G;
;               if (u < TOT) { const WDesc d = wdesc(p, l, u); const LAS float* Tj = T + j * 4160; u32x4 w;
;                   w.x = cvtpk(Tj[(kg + 0) * 65 + r], Tj[(kg + 1) * 65 + r]); w.y = cvtpk(Tj[(kg + 2) * 65 + r], Tj[(kg + 3) * 65 + r]);
;                   w.z = cvtpk(Tj[(kg + 4) * 65 + r], Tj[(kg + 5) * 65 + r]); w.w = cvtpk(Tj[(kg + 6) * 65 + r], Tj[(kg + 7) * 65 + r]);
;                   *(u32x4*)(d.dst + (size_t)(d.r0 + r) * d.lddst + d.k0 + kg) = w; } } }
.Lwt_s3:
	global_store_dwordx4 v21, v[44:47], s[44:45]
	s_add_u32 s44, s44, s1
	s_addc_u32 s45, s45, 0
	s_waitcnt lgkmcnt(0)
	s_cmp_lt_u32 s34, 6
	s_cbranch_scc1 .Lwt_n4
	ds_read_b32 v32, v17
	ds_read_b32 v33, v17 offset:256
	ds_read_b32 v34, v17 offset:512
	ds_read_b32 v35, v17 offset:768
	ds_read_b32 v36, v17 offset:1024
	ds_read_b32 v37, v17 offset:1280
	ds_read_b32 v38, v17 offset:1536
	ds_read_b32 v39, v17 offset:1792
.Lwt_n4:
	s_cmp_lt_u32 s34, 5
	s_cbranch_scc1 .Lwt_z4
	v_cvt_pk_bf16_f32 v40, v24, v25
	v_cvt_pk_bf16_f32 v41, v26, v27
	v_cvt_pk_bf16_f32 v42, v28, v29
	v_cvt_pk_bf16_f32 v43, v30, v31
	s_branch .Lwt_s4

; #define LAS __attribute__((address_space(3)))
; __device__ __forceinline__ unsigned cvtpk(float lo, float hi) { const f32x2 v = (f32x2){lo, hi}; const bf16v2 b = __builtin_convertvector(v, bf16v2); return __builtin_bit_cast(unsigned, b); }
; __device__ void phase_weights(const Params& p, int l, LAS unsigned char* lds) {
;     ...
;         { const int r = tid >> 3, kg = (tid & 7) * 8;
; #pragma unroll
;           for (int j = 0; j < 4; ++j) { const int u = u0 + j * G;
;               if (u < TOT) { const WDesc d = wdesc(p, l, u); const LAS float* Tj = T + j * 4160; u32x4 w;
;                   w.x = cvtpk(Tj[(kg + 0) * 65 + r], Tj[(kg + 1) * 65 + r]); w.y = cvtpk(Tj[(kg + 2) * 65 + r], Tj[(kg + 3) * 65 + r]);
;                   w.z = cvtpk(Tj[(kg + 4) * 65 + r], Tj[(kg + 5) * 65 + r]); w.w = cvtpk(Tj[(kg + 6) * 65 + r], Tj[(kg + 7) * 65 + r]);
;                   *(u32x4*)(d.dst + (size_t)(d.r0 + r) * d.lddst + d.k0 + kg) = w; } } }
.Lwt_s4:
	global_store_dwordx4 v21, v[40:43], s[44:45]
	s_add_u32 s44, s44, s1
	s_addc_u32 s45, s45, 0
	s_waitcnt lgkmcnt(0)
	s_cmp_lt_u32 s34, 7
	s_cbranch_scc1 .Lwt_n5
	ds_read_b32 v24, v18
	ds_read_b32 v25, v18 offset:256
	ds_read_b32 v26, v18 offset:512
	ds_read_b32 v27, v18 offset:768
	ds_read_b32 v28, v18 offset:1024
	ds_read_b32 v29, v18 offset:1280
	ds_read_b32 v30, v18 offset:1536
	ds_read_b32 v31, v18 offset:1792
.Lwt_n5:
	s_cmp_lt_u32 s34, 6
	s_cbranch_scc1 .Lwt_z5
	v_cvt_pk_bf16_f32 v44, v32, v33
	v_cvt_pk_bf16_f32 v45, v34, v35
	v_cvt_pk_bf16_f32 v46, v36, v37
	v_cvt_pk_bf16_f32 v47, v38, v39
	s_branch .Lwt_s5

; #define LAS __attribute__((address_space(3)))
; __device__ __forceinline__ unsigned cvtpk(float lo, float hi) { const f32x2 v = (f32x2){lo, hi}; const bf16v2 b = __builtin_convertvector(v, bf16v2); return __builtin_bit_cast(unsigned, b); }
; __device__ void phase_weights(const Params& p, int l, LAS unsigned char* lds) {
;     ...
;         { const int r = tid >> 3, kg = (tid & 7) * 8;
; #pragma unroll
;           for (int j = 0; j < 4; ++j) { const int u = u0 + j * G;
;               if (u < TOT) { const WDesc d = wdesc(p, l, u); const LAS float* Tj = T + j * 4160; u32x4 w;
;                   w.x = cvtpk(Tj[(kg + 0) * 65 + r], Tj[(kg + 1) * 65 + r]); w.y = cvtpk(Tj[(kg + 2) * 65 + r], Tj[(kg + 3) * 65 + r]);
;                   w.z = cvtpk(Tj[(kg + 4) * 65 + r], Tj[(kg + 5) * 65 + r]); w.w = cvtpk(Tj[(kg + 6) * 65 + r], Tj[(kg + 7) * 65 + r]);
;                   *(u32x4*)(d.dst + (size_t)(d.r0 + r) * d.lddst + d.k0 + kg) = w; } } }
.Lwt_s5:
	global_store_dwordx4 v21, v[44:47], s[44:45]
	s_add_u32 s44, s44, s1
	s_addc_u32 s45, s45, 0
	s_waitcnt lgkmcnt(0)
	s_cmp_lt_u32 s34, 8
	s_cbranch_scc1 .Lwt_n6
	ds_read_b32 v32, v19
	ds_read_b32 v33, v19 offset:256
	ds_read_b32 v34, v19 offset:512
	ds_read_b32 v35, v19 offset:768
	ds_read_b32 v36, v19 offset:1024
	ds_read_b32 v37, v19 offset:1280
	ds_read_b32 v38, v19 offset:1536
	ds_read_b32 v39, v19 offset:1792
.Lwt_n6:
	s_cmp_lt_u32 s34, 7
	s_cbranch_scc1 .Lwt_z6
	v_cvt_pk_bf16_f32 v40, v24, v25
	v_cvt_pk_bf16_f32 v41, v26, v27
	v_cvt_pk_bf16_f32 v42, v28, v29
	v_cvt_pk_bf16_f32 v43, v30, v31
	s_branch .Lwt_s6

; #define LAS __attribute__((address_space(3)))
; __device__ __forceinline__ unsigned cvtpk(float lo, float hi) { const f32x2 v = (f32x2){lo, hi}; const bf16v2 b = __builtin_convertvector(v, bf16v2); return __builtin_bit_cast(unsigned, b); }
; __device__ void phase_weights(const Params& p, int l, LAS unsigned char* lds) {
;     ...
;         { const int r = tid >> 3, kg = (tid & 7) * 8;
; #pragma unroll
;           for (int j = 0; j < 4; ++j) { const int u = u0 + j * G;
;               if (u < TOT) { const WDesc d = wdesc(p, l, u); const LAS float* Tj = T + j * 4160; u32x4 w;
;                   w.x = cvtpk(Tj[(kg + 0) * 65 + r], Tj[(kg + 1) * 65 + r]); w.y = cvtpk(Tj[(kg + 2) * 65 + r], Tj[(kg + 3) * 65 + r]);
;                   w.z = cvtpk(Tj[(kg + 4) * 65 + r], Tj[(kg + 5) * 65 + r]); w.w = cvtpk(Tj[(kg + 6) * 65 + r], Tj[(kg + 7) * 65 + r]);
;                   *(u32x4*)(d.dst + (size_t)(d.r0 + r) * d.lddst + d.k0 + kg) = w; } } }
.Lwt_s6:
	global_store_dwordx4 v21, v[40:43], s[44:45]
	s_add_u32 s44, s44, s1
	s_addc_u32 s45, s45, 0
	s_waitcnt lgkmcnt(0)
	s_cmp_lt_u32 s34, 8
	s_cbranch_scc1 .Lwt_z7
	v_cvt_pk_bf16_f32 v44, v32, v33
	v_cvt_pk_bf16_f32 v45, v34, v35
	v_cvt_pk_bf16_f32 v46, v36, v37
	v_cvt_pk_bf16_f32 v47, v38, v39
	s_branch .Lwt_s7

; #define LAS __attribute__((address_space(3)))
; __device__ __forceinline__ unsigned cvtpk(float lo, float hi) { const f32x2 v = (f32x2){lo, hi}; const bf16v2 b = __builtin_convertvector(v, bf16v2); return __builtin_bit_cast(unsigned, b); }
; __device__ __forceinline__ int obid() { int t = blockIdx.x; asm volatile("" : "+s"(t)); return t; }
; __device__ void phase_weights(const Params& p, int l, LAS unsigned char* lds) {
;     ...
;     for (int u0 = obid(); u0 < TOT; u0 += 4 * G) {
;         f32x4 v[4][2];
;         { const int k = tid >> 3, cg8 = (tid & 7) * 8;
; #pragma unroll
;           for (int j = 0; j < 4; ++j) { const int u = u0 + j * G; v[j][0] = (f32x4){0.f, 0.f, 0.f, 0.f}; v[j][1] = v[j][0];
;               if (u < TOT) { const WDesc d = wdesc(p, l, u); const float* sp = d.src + (size_t)(d.k0 + k) * d.ldsrc + d.c0 + cg8;
;                   if (cg8 + 3 < d.nvalid) v[j][0] = __builtin_nontemporal_load((const f32x4*)sp); if (cg8 + 7 < d.nvalid) v[j][1] = __builtin_nontemporal_load((const f32x4*)(sp + 4)); } }
; #pragma unroll
;           for (int j = 0; j < 4; ++j)
; #pragma unroll
;               for (int i = 0; i < 2; ++i) { LAS float* Tj = T + j * 4160 + k * 65 + cg8 + 4 * i; Tj[0] = v[j][i][0]; Tj[1] = v[j][i][1]; Tj[2] = v[j][i][2]; Tj[3] = v[j][i][3]; } }
;         __syncthreads();
;         { const int r = tid >> 3, kg = (tid & 7) * 8;
; #pragma unroll
;           for (int j = 0; j < 4; ++j) { const int u = u0 + j * G;
;               if (u < TOT) { const WDesc d = wdesc(p, l, u); const LAS float* Tj = T + j * 4160; u32x4 w;
;                   w.x = cvtpk(Tj[(kg + 0) * 65 + r], Tj[(kg + 1) * 65 + r]); w.y = cvtpk(Tj[(kg + 2) * 65 + r], Tj[(kg + 3) * 65 + r]);
;                   w.z = cvtpk(Tj[(kg + 4) * 65 + r], Tj[(kg + 5) * 65 + r]); w.w = cvtpk(Tj[(kg + 6) * 65 + r], Tj[(kg + 7) * 65 + r]);
;                   *(u32x4*)(d.dst + (size_t)(d.r0 + r) * d.lddst + d.k0 + kg) = w; } } }
;         __syncthreads();
;     }
.Lwt_s7:
	global_store_dwordx4 v21, v[44:47], s[44:45]
	s_add_u32 s27, s27, 1
	s_cmp_lt_u32 s27, 2
	s_cbranch_scc1 .Lwt_round
.Lwt_done:
	s_waitcnt lgkmcnt(0)
